# attention work queue: one coherent snapshot of all 8 queue counters when own queue runs dry, exhausted queues skipped without atomic round trips
# speedup vs baseline: 1.0174x; 1.0026x over previous
; __device__ __forceinline__ void phase3(const Params& p, unsigned char* smem, unsigned* bar) {
;     ...
;   int* cnt = (int*)(p.ws + OFF_CTL);
;   const float lam = ((const float*)(p.ws + OFF_CTL))[16];
;   const int myq = blockIdx.x & 7;
;   for (int qq = 0; qq < 8; ++qq) {
;     const int q = (myq + qq) & 7;
.LBB0_320:
	s_setprio 0
	s_mov_b32 s92, 0
	s_cmpk_lt_u32 s89, 0x100
	s_cbranch_scc1 .Lprio_b
	s_setprio 1

; __device__ __forceinline__ void phase3(const Params& p, unsigned char* smem, unsigned* bar) {
;     ...
;   for (int qq = 0; qq < 8; ++qq) {
;     const int q = (myq + qq) & 7;
;     while (true) {
;       if (tid == 0) s_item = atomicAdd(&cnt[q], 1);
;       __syncthreads();
;       const int idx = s_item;
;       __syncthreads();
;       if (idx >= 256) break;
;       attn_item(p, smem, idx & 1, q, 127 - (idx >> 1), lam);
;     }
;   }
.LBB0_321:
	s_add_i32 s43, s43, 1
	s_cmp_lg_u32 s43, 8
	s_cbranch_scc0 .LBB0_346
	s_cmp_lg_u32 s92, 0
	s_cbranch_scc1 .Lq_have
	s_and_saveexec_b64 s[14:15], s[4:5]
	s_cbranch_execz .Lq_snap_done
	s_mov_b32 s16, s35
	s_mov_b32 s17, s38
	global_load_dwordx4 v[96:99], v179, s[16:17] sc1
	global_load_dwordx4 v[100:103], v179, s[16:17] offset:16 sc1
	v_mov_b32_e32 v104, 0x100
	s_waitcnt vmcnt(0)
	v_cmp_lt_u32_e32 vcc, s2, v96
	s_nop 1
	v_cndmask_b32_e64 v105, 0, 1, vcc
	v_lshl_or_b32 v104, v105, 0, v104
	v_cmp_lt_u32_e32 vcc, s2, v97
	s_nop 1
	v_cndmask_b32_e64 v105, 0, 1, vcc
	v_lshl_or_b32 v104, v105, 1, v104
	v_cmp_lt_u32_e32 vcc, s2, v98
	s_nop 1
	v_cndmask_b32_e64 v105, 0, 1, vcc
	v_lshl_or_b32 v104, v105, 2, v104
	v_cmp_lt_u32_e32 vcc, s2, v99
	s_nop 1
	v_cndmask_b32_e64 v105, 0, 1, vcc
	v_lshl_or_b32 v104, v105, 3, v104
	v_cmp_lt_u32_e32 vcc, s2, v100
	s_nop 1
	v_cndmask_b32_e64 v105, 0, 1, vcc
	v_lshl_or_b32 v104, v105, 4, v104
	v_cmp_lt_u32_e32 vcc, s2, v101
	s_nop 1
	v_cndmask_b32_e64 v105, 0, 1, vcc
	v_lshl_or_b32 v104, v105, 5, v104
	v_cmp_lt_u32_e32 vcc, s2, v102
	s_nop 1
	v_cndmask_b32_e64 v105, 0, 1, vcc
	v_lshl_or_b32 v104, v105, 6, v104
	v_cmp_lt_u32_e32 vcc, s2, v103
	s_nop 1
	v_cndmask_b32_e64 v105, 0, 1, vcc
	v_lshl_or_b32 v104, v105, 7, v104
	ds_write_b32 v179, v104 offset:4
.Lq_snap_done:
	s_or_b64 exec, exec, s[14:15]
	s_waitcnt lgkmcnt(0)
	s_barrier
	ds_read_b32 v104, v179 offset:4
	s_waitcnt lgkmcnt(0)
	v_readfirstlane_b32 s92, v104
	s_nop 3
.Lq_have:
	s_add_i32 s8, s43, s89
	s_and_b32 s8, s8, 7
	s_lshr_b32 s8, s92, s8
	s_bitcmp1_b32 s8, 0
	s_cbranch_scc1 .LBB0_321
